# P1 K-loop: sub-tile global loads issued A,A,A,A,B,B,B,B instead of interleaved A,B
# speedup vs baseline: 1.0074x; 1.0074x over previous
; DI int TID() { int t = threadIdx.x; asm volatile("" : "+v"(t)); return t; }
; #define GEMM_GLOAD(P, kt_) { GEMM_GL1(P, 0, kt_) GEMM_GL1(P, 1, kt_) GEMM_GL1(P, 2, kt_) GEMM_GL1(P, 3, kt_) }
; #define GEMM_LSTORE(P, buf_) { GEMM_LS1(P, 0, buf_) GEMM_LS1(P, 1, buf_) GEMM_LS1(P, 2, buf_) GEMM_LS1(P, 3, buf_) }
; template <bool DEEP>
; DI void gemm_mainloop_t(const u16* __restrict__ Ag, int lda, const u16* __restrict__ Bg, int ldb, int K, char* ldsraw,
;                         f32x16 (&acc)[2][2], int akstep) {
;   const int tid = TID(), lane = tid & 63, w = tid >> 6, wm = w >> 1, wn = w & 1, r = lane & 31, h = lane >> 5;
;   u16* As = (u16*)ldsraw;
;   u16* Bs = As + 2 * 128 * LDT;
;   uint4 xa0, xa1, xa2, xa3, xb0, xb1, xb2, xb3;
;   const int nk = K >> 6;
;   const int row0 = tid >> 3, cc = tid & 7;
;   if (DEEP) {
;     uint4 ya0, ya1, ya2, ya3, yb0, yb1, yb2, yb3;
;     GEMM_GLOAD(x, 0);
;     GEMM_GLOAD(y, 1);
;     GEMM_LSTORE(x, 0);
;     __syncthreads();
;     for (int kt = 0; kt < nk; kt += 2) {
;       if (kt + 2 < nk) GEMM_GLOAD(x, kt + 2);
;       GEMM_COMPUTE(0);
;       GEMM_LSTORE(y, 1);
;       __syncthreads();
;       if (kt + 3 < nk) GEMM_GLOAD(y, kt + 3);
;       GEMM_COMPUTE(1);
;       if (kt + 2 < nk) GEMM_LSTORE(x, 0);
;       __syncthreads();
;     }
; DI void phase1(const Params& p, int l, char* lds) {
;     ...
;   for (int tile = blockIdx.x; tile < 128 * 51; tile += gridDim.x) {
;     const int grp = tile / (32 * 51), rem = tile % (32 * 51);
;     const int nt = rem >> 5, mt = grp * 32 + (rem & 31);
;     f32x16 acc[2][2];
;     zero_acc(acc);
;     gemm_mainloop(p.xn + (size_t)mt * 128 * 1024, 1024, WINT(l) + (size_t)nt * 128 * 1024, 1024, 1024, lds, acc);
.LBB0_219:
	s_mul_hi_i32 s0, s3, 0xa0a0a0a1
	s_add_i32 s0, s0, s3
	s_lshr_b32 s1, s0, 31
	s_ashr_i32 s0, s0, 10
	s_add_i32 s1, s0, s1
	s_mul_i32 s0, s1, 0xfffff9a0
	s_add_i32 s18, s3, s0
	s_lshl_b32 s1, s1, 5
	s_and_b32 s12, s18, 31
	s_or_b32 s12, s1, s12
	s_ashr_i32 s13, s12, 31
	s_ashr_i32 s0, s18, 5
	s_lshl_b64 s[14:15], s[12:13], 18
	s_waitcnt vmcnt(31)
	s_add_u32 s14, s88, s14
	s_addc_u32 s15, s89, s15
	s_ashr_i32 s1, s0, 31
	s_lshl_b64 s[16:17], s[0:1], 18
	s_add_u32 s16, s20, s16
	s_addc_u32 s17, s21, s17
	v_lshrrev_b32_e32 v146, 3, v209
	v_and_b32_e32 v147, 7, v209
	v_lshlrev_b32_e32 v147, 4, v147
	v_mov_b32_e32 v148, v146
	v_mul_u32_u24_e32 v134, 0x800, v148
	v_add_u32_e32 v134, v134, v147
	v_mul_u32_u24_e32 v138, 0x800, v148
	v_add_u32_e32 v138, v138, v147
	v_add_u32_e32 v148, 32, v146
	v_mul_u32_u24_e32 v135, 0x800, v148
	v_add_u32_e32 v135, v135, v147
	v_mul_u32_u24_e32 v139, 0x800, v148
	v_add_u32_e32 v139, v139, v147
	v_add_u32_e32 v148, 64, v146
	v_mul_u32_u24_e32 v136, 0x800, v148
	v_add_u32_e32 v136, v136, v147
	v_mul_u32_u24_e32 v140, 0x800, v148
	v_add_u32_e32 v140, v140, v147
	v_add_u32_e32 v148, 96, v146
	v_mul_u32_u24_e32 v137, 0x800, v148
	v_add_u32_e32 v137, v137, v147
	v_mul_u32_u24_e32 v141, 0x800, v148
	v_add_u32_e32 v141, v141, v147
	v_mul_u32_u24_e32 v142, 0x90, v146
	v_add_u32_e32 v142, v142, v147
	v_add_u32_e32 v143, 0x1200, v142
	v_and_b32_e32 v146, 31, v209
	v_bfe_u32 v147, v209, 5, 1
	v_lshlrev_b32_e32 v147, 4, v147
	v_bfe_u32 v148, v209, 7, 1
	v_lshl_add_u32 v148, v148, 6, v146
	v_mul_u32_u24_e32 v144, 0x90, v148
	v_add_u32_e32 v144, v144, v147
	v_bfe_u32 v148, v209, 6, 1
	v_lshl_add_u32 v148, v148, 6, v146
	v_mul_u32_u24_e32 v145, 0x90, v148
	v_add_u32_e32 v145, v145, v147
	global_load_dwordx4 v[66:69], v134, s[14:15]
	global_load_dwordx4 v[74:77], v135, s[14:15]
	global_load_dwordx4 v[82:85], v136, s[14:15]
	global_load_dwordx4 v[90:93], v137, s[14:15]
	global_load_dwordx4 v[70:73], v138, s[16:17]
	global_load_dwordx4 v[78:81], v139, s[16:17]
	global_load_dwordx4 v[86:89], v140, s[16:17]
	global_load_dwordx4 v[94:97], v141, s[16:17]
	global_load_dwordx4 v[98:101], v134, s[14:15] offset:128
	global_load_dwordx4 v[106:109], v135, s[14:15] offset:128
	global_load_dwordx4 v[114:117], v136, s[14:15] offset:128
	global_load_dwordx4 v[122:125], v137, s[14:15] offset:128
	global_load_dwordx4 v[102:105], v138, s[16:17] offset:128
	global_load_dwordx4 v[110:113], v139, s[16:17] offset:128
	global_load_dwordx4 v[118:121], v140, s[16:17] offset:128
	global_load_dwordx4 v[126:129], v141, s[16:17] offset:128
	s_waitcnt vmcnt(15)
	ds_write_b128 v142, v[66:69]
	s_waitcnt vmcnt(14)
	ds_write_b128 v142, v[74:77] offset:4608
	s_waitcnt vmcnt(13)
	ds_write_b128 v142, v[82:85] offset:9216
	s_waitcnt vmcnt(12)
	ds_write_b128 v142, v[90:93] offset:13824
	s_waitcnt vmcnt(11)
	ds_write_b128 v142, v[70:73] offset:36864
	s_waitcnt vmcnt(10)
	ds_write_b128 v142, v[78:81] offset:41472
	s_waitcnt vmcnt(9)
	ds_write_b128 v142, v[86:89] offset:46080
	s_waitcnt vmcnt(8)
	ds_write_b128 v142, v[94:97] offset:50688
	s_waitcnt lgkmcnt(0)
	s_barrier
	s_setprio 1
	ds_read_b128 v[156:159], v145 offset:36864
	ds_read_b128 v[160:163], v144
	ds_read_b128 v[164:167], v145 offset:41472
	ds_read_b128 v[168:171], v144 offset:4608
	s_waitcnt lgkmcnt(2)
	v_mfma_f32_32x32x16_f16 v[50:65], v[156:159], v[160:163], 0
	global_load_dwordx4 v[66:69], v134, s[14:15] offset:256
	s_waitcnt lgkmcnt(1)
	v_mfma_f32_32x32x16_f16 v[34:49], v[164:167], v[160:163], 0
	ds_read_b128 v[160:163], v144 offset:32
	s_waitcnt vmcnt(8)
	ds_write_b128 v142, v[98:101] offset:18432
	s_waitcnt lgkmcnt(2)
	v_mfma_f32_32x32x16_f16 v[18:33], v[156:159], v[168:171], 0
	ds_read_b128 v[156:159], v145 offset:36896
	global_load_dwordx4 v[74:77], v135, s[14:15] offset:256
	v_mfma_f32_32x32x16_f16 v[2:17], v[164:167], v[168:171], 0
	ds_read_b128 v[164:167], v145 offset:41504
	ds_read_b128 v[168:171], v144 offset:4640
	s_waitcnt vmcnt(8)
	ds_write_b128 v142, v[106:109] offset:23040
	s_waitcnt lgkmcnt(3)
	v_mfma_f32_32x32x16_f16 v[50:65], v[156:159], v[160:163], v[50:65]
	global_load_dwordx4 v[82:85], v136, s[14:15] offset:256
	s_waitcnt lgkmcnt(2)
	v_mfma_f32_32x32x16_f16 v[34:49], v[164:167], v[160:163], v[34:49]
	ds_read_b128 v[160:163], v144 offset:64
	s_waitcnt vmcnt(8)
	ds_write_b128 v142, v[114:117] offset:27648
	s_waitcnt lgkmcnt(3)
	v_mfma_f32_32x32x16_f16 v[18:33], v[156:159], v[168:171], v[18:33]
	ds_read_b128 v[156:159], v145 offset:36928
	global_load_dwordx4 v[90:93], v137, s[14:15] offset:256
	v_mfma_f32_32x32x16_f16 v[2:17], v[164:167], v[168:171], v[2:17]
	ds_read_b128 v[164:167], v145 offset:41536
	ds_read_b128 v[168:171], v144 offset:4672
	s_waitcnt vmcnt(8)
	ds_write_b128 v142, v[122:125] offset:32256
	s_waitcnt lgkmcnt(3)
	v_mfma_f32_32x32x16_f16 v[50:65], v[156:159], v[160:163], v[50:65]
	global_load_dwordx4 v[70:73], v138, s[16:17] offset:256
	s_waitcnt lgkmcnt(2)
	v_mfma_f32_32x32x16_f16 v[34:49], v[164:167], v[160:163], v[34:49]
	ds_read_b128 v[160:163], v144 offset:96
	s_waitcnt vmcnt(8)
	ds_write_b128 v142, v[102:105] offset:55296
	s_waitcnt lgkmcnt(3)
	v_mfma_f32_32x32x16_f16 v[18:33], v[156:159], v[168:171], v[18:33]
	ds_read_b128 v[156:159], v145 offset:36960
	global_load_dwordx4 v[78:81], v139, s[16:17] offset:256
	v_mfma_f32_32x32x16_f16 v[2:17], v[164:167], v[168:171], v[2:17]
	ds_read_b128 v[164:167], v145 offset:41568
	ds_read_b128 v[168:171], v144 offset:4704
	s_waitcnt vmcnt(8)
	ds_write_b128 v142, v[110:113] offset:59904
	s_waitcnt lgkmcnt(3)
	v_mfma_f32_32x32x16_f16 v[50:65], v[156:159], v[160:163], v[50:65]
	global_load_dwordx4 v[86:89], v140, s[16:17] offset:256
	s_waitcnt lgkmcnt(2)
	v_mfma_f32_32x32x16_f16 v[34:49], v[164:167], v[160:163], v[34:49]
	s_waitcnt vmcnt(8)
	ds_write_b128 v142, v[118:121] offset:64512
	s_waitcnt lgkmcnt(2)
	v_mfma_f32_32x32x16_f16 v[18:33], v[156:159], v[168:171], v[18:33]
	global_load_dwordx4 v[94:97], v141, s[16:17] offset:256
	v_mfma_f32_32x32x16_f16 v[2:17], v[164:167], v[168:171], v[2:17]
	s_waitcnt vmcnt(8)
	ds_write_b128 v143, v[126:129] offset:64512
	s_setprio 0
	s_waitcnt lgkmcnt(0)
	s_barrier
; #define GEMM_GLOAD(P, kt_) { GEMM_GL1(P, 0, kt_) GEMM_GL1(P, 1, kt_) GEMM_GL1(P, 2, kt_) GEMM_GL1(P, 3, kt_) }
; #define GEMM_LSTORE(P, buf_) { GEMM_LS1(P, 0, buf_) GEMM_LS1(P, 1, buf_) GEMM_LS1(P, 2, buf_) GEMM_LS1(P, 3, buf_) }
; template <bool DEEP>
; DI void gemm_mainloop_t(const u16* __restrict__ Ag, int lda, const u16* __restrict__ Bg, int ldb, int K, char* ldsraw,
;                         f32x16 (&acc)[2][2], int akstep) {
;     ...
;     for (int kt = 0; kt < nk; kt += 2) {
;       if (kt + 2 < nk) GEMM_GLOAD(x, kt + 2);
;       GEMM_COMPUTE(0);
;       GEMM_LSTORE(y, 1);
;       __syncthreads();
;       if (kt + 3 < nk) GEMM_GLOAD(y, kt + 3);
;       GEMM_COMPUTE(1);
;       if (kt + 2 < nk) GEMM_LSTORE(x, 0);
;       __syncthreads();
;     }
	s_setprio 1
	ds_read_b128 v[156:159], v145 offset:55296
	ds_read_b128 v[160:163], v144 offset:18432
	ds_read_b128 v[164:167], v145 offset:59904
	ds_read_b128 v[168:171], v144 offset:23040
	s_waitcnt lgkmcnt(2)
	v_mfma_f32_32x32x16_f16 v[50:65], v[156:159], v[160:163], v[50:65]
	global_load_dwordx4 v[98:101], v134, s[14:15] offset:384
	s_waitcnt lgkmcnt(1)
	v_mfma_f32_32x32x16_f16 v[34:49], v[164:167], v[160:163], v[34:49]
	ds_read_b128 v[160:163], v144 offset:18464
	s_waitcnt vmcnt(8)
	ds_write_b128 v142, v[66:69]
	s_waitcnt lgkmcnt(2)
	v_mfma_f32_32x32x16_f16 v[18:33], v[156:159], v[168:171], v[18:33]
	ds_read_b128 v[156:159], v145 offset:55328
	global_load_dwordx4 v[106:109], v135, s[14:15] offset:384
	v_mfma_f32_32x32x16_f16 v[2:17], v[164:167], v[168:171], v[2:17]
	ds_read_b128 v[164:167], v145 offset:59936
	ds_read_b128 v[168:171], v144 offset:23072
	s_waitcnt vmcnt(8)
	ds_write_b128 v142, v[74:77] offset:4608
	s_waitcnt lgkmcnt(3)
	v_mfma_f32_32x32x16_f16 v[50:65], v[156:159], v[160:163], v[50:65]
	global_load_dwordx4 v[114:117], v136, s[14:15] offset:384
	s_waitcnt lgkmcnt(2)
	v_mfma_f32_32x32x16_f16 v[34:49], v[164:167], v[160:163], v[34:49]
	ds_read_b128 v[160:163], v144 offset:18496
	s_waitcnt vmcnt(8)
	ds_write_b128 v142, v[82:85] offset:9216
	s_waitcnt lgkmcnt(3)
	v_mfma_f32_32x32x16_f16 v[18:33], v[156:159], v[168:171], v[18:33]
	ds_read_b128 v[156:159], v145 offset:55360
	global_load_dwordx4 v[122:125], v137, s[14:15] offset:384
	v_mfma_f32_32x32x16_f16 v[2:17], v[164:167], v[168:171], v[2:17]
	ds_read_b128 v[164:167], v145 offset:59968
	ds_read_b128 v[168:171], v144 offset:23104
	s_waitcnt vmcnt(8)
	ds_write_b128 v142, v[90:93] offset:13824
	s_waitcnt lgkmcnt(3)
	v_mfma_f32_32x32x16_f16 v[50:65], v[156:159], v[160:163], v[50:65]
	global_load_dwordx4 v[102:105], v138, s[16:17] offset:384
	s_waitcnt lgkmcnt(2)
	v_mfma_f32_32x32x16_f16 v[34:49], v[164:167], v[160:163], v[34:49]
	ds_read_b128 v[160:163], v144 offset:18528
	s_waitcnt vmcnt(8)
	ds_write_b128 v142, v[70:73] offset:36864
	s_waitcnt lgkmcnt(3)
	v_mfma_f32_32x32x16_f16 v[18:33], v[156:159], v[168:171], v[18:33]
	ds_read_b128 v[156:159], v145 offset:55392
	global_load_dwordx4 v[110:113], v139, s[16:17] offset:384
	v_mfma_f32_32x32x16_f16 v[2:17], v[164:167], v[168:171], v[2:17]
	ds_read_b128 v[164:167], v145 offset:60000
	ds_read_b128 v[168:171], v144 offset:23136
	s_waitcnt vmcnt(8)
	ds_write_b128 v142, v[78:81] offset:41472
	s_waitcnt lgkmcnt(3)
	v_mfma_f32_32x32x16_f16 v[50:65], v[156:159], v[160:163], v[50:65]
	global_load_dwordx4 v[118:121], v140, s[16:17] offset:384
	s_waitcnt lgkmcnt(2)
	v_mfma_f32_32x32x16_f16 v[34:49], v[164:167], v[160:163], v[34:49]
	s_waitcnt vmcnt(8)
	ds_write_b128 v142, v[86:89] offset:46080
	s_waitcnt lgkmcnt(2)
	v_mfma_f32_32x32x16_f16 v[18:33], v[156:159], v[168:171], v[18:33]
	global_load_dwordx4 v[126:129], v141, s[16:17] offset:384
	v_mfma_f32_32x32x16_f16 v[2:17], v[164:167], v[168:171], v[2:17]
	s_waitcnt vmcnt(8)
	ds_write_b128 v142, v[94:97] offset:50688
	s_setprio 0
	s_waitcnt lgkmcnt(0)
	s_barrier
	s_setprio 1
	ds_read_b128 v[156:159], v145 offset:36864
	ds_read_b128 v[160:163], v144
	ds_read_b128 v[164:167], v145 offset:41472
	ds_read_b128 v[168:171], v144 offset:4608
	s_waitcnt lgkmcnt(2)
	v_mfma_f32_32x32x16_f16 v[50:65], v[156:159], v[160:163], v[50:65]
	global_load_dwordx4 v[66:69], v134, s[14:15] offset:512
	s_waitcnt lgkmcnt(1)
	v_mfma_f32_32x32x16_f16 v[34:49], v[164:167], v[160:163], v[34:49]
	ds_read_b128 v[160:163], v144 offset:32
	s_waitcnt vmcnt(8)
	ds_write_b128 v142, v[98:101] offset:18432
	s_waitcnt lgkmcnt(2)
	v_mfma_f32_32x32x16_f16 v[18:33], v[156:159], v[168:171], v[18:33]
	ds_read_b128 v[156:159], v145 offset:36896
	global_load_dwordx4 v[74:77], v135, s[14:15] offset:512
	v_mfma_f32_32x32x16_f16 v[2:17], v[164:167], v[168:171], v[2:17]
	ds_read_b128 v[164:167], v145 offset:41504
	ds_read_b128 v[168:171], v144 offset:4640
	s_waitcnt vmcnt(8)
	ds_write_b128 v142, v[106:109] offset:23040
	s_waitcnt lgkmcnt(3)
	v_mfma_f32_32x32x16_f16 v[50:65], v[156:159], v[160:163], v[50:65]
	global_load_dwordx4 v[82:85], v136, s[14:15] offset:512
	s_waitcnt lgkmcnt(2)
	v_mfma_f32_32x32x16_f16 v[34:49], v[164:167], v[160:163], v[34:49]
	ds_read_b128 v[160:163], v144 offset:64
	s_waitcnt vmcnt(8)
	ds_write_b128 v142, v[114:117] offset:27648
	s_waitcnt lgkmcnt(3)
	v_mfma_f32_32x32x16_f16 v[18:33], v[156:159], v[168:171], v[18:33]
	ds_read_b128 v[156:159], v145 offset:36928
	global_load_dwordx4 v[90:93], v137, s[14:15] offset:512
	v_mfma_f32_32x32x16_f16 v[2:17], v[164:167], v[168:171], v[2:17]
	ds_read_b128 v[164:167], v145 offset:41536
	ds_read_b128 v[168:171], v144 offset:4672
	s_waitcnt vmcnt(8)
	ds_write_b128 v142, v[122:125] offset:32256
	s_waitcnt lgkmcnt(3)
	v_mfma_f32_32x32x16_f16 v[50:65], v[156:159], v[160:163], v[50:65]
	global_load_dwordx4 v[70:73], v138, s[16:17] offset:512
	s_waitcnt lgkmcnt(2)
	v_mfma_f32_32x32x16_f16 v[34:49], v[164:167], v[160:163], v[34:49]
	ds_read_b128 v[160:163], v144 offset:96
	s_waitcnt vmcnt(8)
	ds_write_b128 v142, v[102:105] offset:55296
	s_waitcnt lgkmcnt(3)
	v_mfma_f32_32x32x16_f16 v[18:33], v[156:159], v[168:171], v[18:33]
	ds_read_b128 v[156:159], v145 offset:36960
	global_load_dwordx4 v[78:81], v139, s[16:17] offset:512
	v_mfma_f32_32x32x16_f16 v[2:17], v[164:167], v[168:171], v[2:17]
	ds_read_b128 v[164:167], v145 offset:41568
	ds_read_b128 v[168:171], v144 offset:4704
	s_waitcnt vmcnt(8)
	ds_write_b128 v142, v[110:113] offset:59904
	s_waitcnt lgkmcnt(3)
	v_mfma_f32_32x32x16_f16 v[50:65], v[156:159], v[160:163], v[50:65]
	global_load_dwordx4 v[86:89], v140, s[16:17] offset:512
	s_waitcnt lgkmcnt(2)
	v_mfma_f32_32x32x16_f16 v[34:49], v[164:167], v[160:163], v[34:49]
	s_waitcnt vmcnt(8)
	ds_write_b128 v142, v[118:121] offset:64512
	s_waitcnt lgkmcnt(2)
	v_mfma_f32_32x32x16_f16 v[18:33], v[156:159], v[168:171], v[18:33]
	global_load_dwordx4 v[94:97], v141, s[16:17] offset:512
	v_mfma_f32_32x32x16_f16 v[2:17], v[164:167], v[168:171], v[2:17]
	s_waitcnt vmcnt(8)
	ds_write_b128 v143, v[126:129] offset:64512
	s_setprio 0
	s_waitcnt lgkmcnt(0)
	s_barrier
; #define GEMM_GLOAD(P, kt_) { GEMM_GL1(P, 0, kt_) GEMM_GL1(P, 1, kt_) GEMM_GL1(P, 2, kt_) GEMM_GL1(P, 3, kt_) }
; #define GEMM_LSTORE(P, buf_) { GEMM_LS1(P, 0, buf_) GEMM_LS1(P, 1, buf_) GEMM_LS1(P, 2, buf_) GEMM_LS1(P, 3, buf_) }
; template <bool DEEP>
; DI void gemm_mainloop_t(const u16* __restrict__ Ag, int lda, const u16* __restrict__ Bg, int ldb, int K, char* ldsraw,
;                         f32x16 (&acc)[2][2], int akstep) {
;     ...
;     for (int kt = 0; kt < nk; kt += 2) {
;       if (kt + 2 < nk) GEMM_GLOAD(x, kt + 2);
;       GEMM_COMPUTE(0);
;       GEMM_LSTORE(y, 1);
;       __syncthreads();
;       if (kt + 3 < nk) GEMM_GLOAD(y, kt + 3);
;       GEMM_COMPUTE(1);
;       if (kt + 2 < nk) GEMM_LSTORE(x, 0);
;       __syncthreads();
;     }
	s_setprio 1
	ds_read_b128 v[156:159], v145 offset:55296
	ds_read_b128 v[160:163], v144 offset:18432
	ds_read_b128 v[164:167], v145 offset:59904
	ds_read_b128 v[168:171], v144 offset:23040
	s_waitcnt lgkmcnt(2)
	v_mfma_f32_32x32x16_f16 v[50:65], v[156:159], v[160:163], v[50:65]
	global_load_dwordx4 v[98:101], v134, s[14:15] offset:640
	s_waitcnt lgkmcnt(1)
	v_mfma_f32_32x32x16_f16 v[34:49], v[164:167], v[160:163], v[34:49]
	ds_read_b128 v[160:163], v144 offset:18464
	s_waitcnt vmcnt(8)
	ds_write_b128 v142, v[66:69]
	s_waitcnt lgkmcnt(2)
	v_mfma_f32_32x32x16_f16 v[18:33], v[156:159], v[168:171], v[18:33]
	ds_read_b128 v[156:159], v145 offset:55328
	global_load_dwordx4 v[106:109], v135, s[14:15] offset:640
	v_mfma_f32_32x32x16_f16 v[2:17], v[164:167], v[168:171], v[2:17]
	ds_read_b128 v[164:167], v145 offset:59936
	ds_read_b128 v[168:171], v144 offset:23072
	s_waitcnt vmcnt(8)
	ds_write_b128 v142, v[74:77] offset:4608
	s_waitcnt lgkmcnt(3)
	v_mfma_f32_32x32x16_f16 v[50:65], v[156:159], v[160:163], v[50:65]
	global_load_dwordx4 v[114:117], v136, s[14:15] offset:640
	s_waitcnt lgkmcnt(2)
	v_mfma_f32_32x32x16_f16 v[34:49], v[164:167], v[160:163], v[34:49]
	ds_read_b128 v[160:163], v144 offset:18496
	s_waitcnt vmcnt(8)
	ds_write_b128 v142, v[82:85] offset:9216
	s_waitcnt lgkmcnt(3)
	v_mfma_f32_32x32x16_f16 v[18:33], v[156:159], v[168:171], v[18:33]
	ds_read_b128 v[156:159], v145 offset:55360
	global_load_dwordx4 v[122:125], v137, s[14:15] offset:640
	v_mfma_f32_32x32x16_f16 v[2:17], v[164:167], v[168:171], v[2:17]
	ds_read_b128 v[164:167], v145 offset:59968
	ds_read_b128 v[168:171], v144 offset:23104
	s_waitcnt vmcnt(8)
	ds_write_b128 v142, v[90:93] offset:13824
	s_waitcnt lgkmcnt(3)
	v_mfma_f32_32x32x16_f16 v[50:65], v[156:159], v[160:163], v[50:65]
	global_load_dwordx4 v[102:105], v138, s[16:17] offset:640
	s_waitcnt lgkmcnt(2)
	v_mfma_f32_32x32x16_f16 v[34:49], v[164:167], v[160:163], v[34:49]
	ds_read_b128 v[160:163], v144 offset:18528
	s_waitcnt vmcnt(8)
	ds_write_b128 v142, v[70:73] offset:36864
	s_waitcnt lgkmcnt(3)
	v_mfma_f32_32x32x16_f16 v[18:33], v[156:159], v[168:171], v[18:33]
	ds_read_b128 v[156:159], v145 offset:55392
	global_load_dwordx4 v[110:113], v139, s[16:17] offset:640
	v_mfma_f32_32x32x16_f16 v[2:17], v[164:167], v[168:171], v[2:17]
	ds_read_b128 v[164:167], v145 offset:60000
	ds_read_b128 v[168:171], v144 offset:23136
	s_waitcnt vmcnt(8)
	ds_write_b128 v142, v[78:81] offset:41472
	s_waitcnt lgkmcnt(3)
	v_mfma_f32_32x32x16_f16 v[50:65], v[156:159], v[160:163], v[50:65]
	global_load_dwordx4 v[118:121], v140, s[16:17] offset:640
	s_waitcnt lgkmcnt(2)
	v_mfma_f32_32x32x16_f16 v[34:49], v[164:167], v[160:163], v[34:49]
	s_waitcnt vmcnt(8)
	ds_write_b128 v142, v[86:89] offset:46080
	s_waitcnt lgkmcnt(2)
	v_mfma_f32_32x32x16_f16 v[18:33], v[156:159], v[168:171], v[18:33]
	global_load_dwordx4 v[126:129], v141, s[16:17] offset:640
	v_mfma_f32_32x32x16_f16 v[2:17], v[164:167], v[168:171], v[2:17]
	s_waitcnt vmcnt(8)
	ds_write_b128 v142, v[94:97] offset:50688
	s_setprio 0
	s_waitcnt lgkmcnt(0)
	s_barrier
	s_setprio 1
	ds_read_b128 v[156:159], v145 offset:36864
	ds_read_b128 v[160:163], v144
	ds_read_b128 v[164:167], v145 offset:41472
	ds_read_b128 v[168:171], v144 offset:4608
	s_waitcnt lgkmcnt(2)
	v_mfma_f32_32x32x16_f16 v[50:65], v[156:159], v[160:163], v[50:65]
	global_load_dwordx4 v[66:69], v134, s[14:15] offset:768
	s_waitcnt lgkmcnt(1)
	v_mfma_f32_32x32x16_f16 v[34:49], v[164:167], v[160:163], v[34:49]
	ds_read_b128 v[160:163], v144 offset:32
	s_waitcnt vmcnt(8)
	ds_write_b128 v142, v[98:101] offset:18432
	s_waitcnt lgkmcnt(2)
	v_mfma_f32_32x32x16_f16 v[18:33], v[156:159], v[168:171], v[18:33]
	ds_read_b128 v[156:159], v145 offset:36896
	global_load_dwordx4 v[74:77], v135, s[14:15] offset:768
	v_mfma_f32_32x32x16_f16 v[2:17], v[164:167], v[168:171], v[2:17]
	ds_read_b128 v[164:167], v145 offset:41504
	ds_read_b128 v[168:171], v144 offset:4640
	s_waitcnt vmcnt(8)
	ds_write_b128 v142, v[106:109] offset:23040
	s_waitcnt lgkmcnt(3)
	v_mfma_f32_32x32x16_f16 v[50:65], v[156:159], v[160:163], v[50:65]
	global_load_dwordx4 v[82:85], v136, s[14:15] offset:768
	s_waitcnt lgkmcnt(2)
	v_mfma_f32_32x32x16_f16 v[34:49], v[164:167], v[160:163], v[34:49]
	ds_read_b128 v[160:163], v144 offset:64
	s_waitcnt vmcnt(8)
	ds_write_b128 v142, v[114:117] offset:27648
	s_waitcnt lgkmcnt(3)
	v_mfma_f32_32x32x16_f16 v[18:33], v[156:159], v[168:171], v[18:33]
	ds_read_b128 v[156:159], v145 offset:36928
	global_load_dwordx4 v[90:93], v137, s[14:15] offset:768
	v_mfma_f32_32x32x16_f16 v[2:17], v[164:167], v[168:171], v[2:17]
	ds_read_b128 v[164:167], v145 offset:41536
	ds_read_b128 v[168:171], v144 offset:4672
	s_waitcnt vmcnt(8)
	ds_write_b128 v142, v[122:125] offset:32256
	s_waitcnt lgkmcnt(3)
	v_mfma_f32_32x32x16_f16 v[50:65], v[156:159], v[160:163], v[50:65]
	global_load_dwordx4 v[70:73], v138, s[16:17] offset:768
	s_waitcnt lgkmcnt(2)
	v_mfma_f32_32x32x16_f16 v[34:49], v[164:167], v[160:163], v[34:49]
	ds_read_b128 v[160:163], v144 offset:96
	s_waitcnt vmcnt(8)
	ds_write_b128 v142, v[102:105] offset:55296
	s_waitcnt lgkmcnt(3)
	v_mfma_f32_32x32x16_f16 v[18:33], v[156:159], v[168:171], v[18:33]
	ds_read_b128 v[156:159], v145 offset:36960
	global_load_dwordx4 v[78:81], v139, s[16:17] offset:768
	v_mfma_f32_32x32x16_f16 v[2:17], v[164:167], v[168:171], v[2:17]
	ds_read_b128 v[164:167], v145 offset:41568
	ds_read_b128 v[168:171], v144 offset:4704
	s_waitcnt vmcnt(8)
	ds_write_b128 v142, v[110:113] offset:59904
	s_waitcnt lgkmcnt(3)
	v_mfma_f32_32x32x16_f16 v[50:65], v[156:159], v[160:163], v[50:65]
	global_load_dwordx4 v[86:89], v140, s[16:17] offset:768
	s_waitcnt lgkmcnt(2)
	v_mfma_f32_32x32x16_f16 v[34:49], v[164:167], v[160:163], v[34:49]
	s_waitcnt vmcnt(8)
	ds_write_b128 v142, v[118:121] offset:64512
	s_waitcnt lgkmcnt(2)
	v_mfma_f32_32x32x16_f16 v[18:33], v[156:159], v[168:171], v[18:33]
	global_load_dwordx4 v[94:97], v141, s[16:17] offset:768
	v_mfma_f32_32x32x16_f16 v[2:17], v[164:167], v[168:171], v[2:17]
	s_waitcnt vmcnt(8)
	ds_write_b128 v143, v[126:129] offset:64512
	s_setprio 0
	s_waitcnt lgkmcnt(0)
	s_barrier
; #define GEMM_GLOAD(P, kt_) { GEMM_GL1(P, 0, kt_) GEMM_GL1(P, 1, kt_) GEMM_GL1(P, 2, kt_) GEMM_GL1(P, 3, kt_) }
; #define GEMM_LSTORE(P, buf_) { GEMM_LS1(P, 0, buf_) GEMM_LS1(P, 1, buf_) GEMM_LS1(P, 2, buf_) GEMM_LS1(P, 3, buf_) }
; template <bool DEEP>
; DI void gemm_mainloop_t(const u16* __restrict__ Ag, int lda, const u16* __restrict__ Bg, int ldb, int K, char* ldsraw,
;                         f32x16 (&acc)[2][2], int akstep) {
;     ...
;     for (int kt = 0; kt < nk; kt += 2) {
;       if (kt + 2 < nk) GEMM_GLOAD(x, kt + 2);
;       GEMM_COMPUTE(0);
;       GEMM_LSTORE(y, 1);
;       __syncthreads();
;       if (kt + 3 < nk) GEMM_GLOAD(y, kt + 3);
;       GEMM_COMPUTE(1);
;       if (kt + 2 < nk) GEMM_LSTORE(x, 0);
;       __syncthreads();
;     }
	s_setprio 1
	ds_read_b128 v[156:159], v145 offset:55296
	ds_read_b128 v[160:163], v144 offset:18432
	ds_read_b128 v[164:167], v145 offset:59904
	ds_read_b128 v[168:171], v144 offset:23040
	s_waitcnt lgkmcnt(2)
	v_mfma_f32_32x32x16_f16 v[50:65], v[156:159], v[160:163], v[50:65]
	global_load_dwordx4 v[98:101], v134, s[14:15] offset:896
	s_waitcnt lgkmcnt(1)
	v_mfma_f32_32x32x16_f16 v[34:49], v[164:167], v[160:163], v[34:49]
	ds_read_b128 v[160:163], v144 offset:18464
	s_waitcnt vmcnt(8)
	ds_write_b128 v142, v[66:69]
	s_waitcnt lgkmcnt(2)
	v_mfma_f32_32x32x16_f16 v[18:33], v[156:159], v[168:171], v[18:33]
	ds_read_b128 v[156:159], v145 offset:55328
	global_load_dwordx4 v[106:109], v135, s[14:15] offset:896
	v_mfma_f32_32x32x16_f16 v[2:17], v[164:167], v[168:171], v[2:17]
	ds_read_b128 v[164:167], v145 offset:59936
	ds_read_b128 v[168:171], v144 offset:23072
	s_waitcnt vmcnt(8)
	ds_write_b128 v142, v[74:77] offset:4608
	s_waitcnt lgkmcnt(3)
	v_mfma_f32_32x32x16_f16 v[50:65], v[156:159], v[160:163], v[50:65]
	global_load_dwordx4 v[114:117], v136, s[14:15] offset:896
	s_waitcnt lgkmcnt(2)
	v_mfma_f32_32x32x16_f16 v[34:49], v[164:167], v[160:163], v[34:49]
	ds_read_b128 v[160:163], v144 offset:18496
	s_waitcnt vmcnt(8)
	ds_write_b128 v142, v[82:85] offset:9216
	s_waitcnt lgkmcnt(3)
	v_mfma_f32_32x32x16_f16 v[18:33], v[156:159], v[168:171], v[18:33]
	ds_read_b128 v[156:159], v145 offset:55360
	global_load_dwordx4 v[122:125], v137, s[14:15] offset:896
	v_mfma_f32_32x32x16_f16 v[2:17], v[164:167], v[168:171], v[2:17]
	ds_read_b128 v[164:167], v145 offset:59968
	ds_read_b128 v[168:171], v144 offset:23104
	s_waitcnt vmcnt(8)
	ds_write_b128 v142, v[90:93] offset:13824
	s_waitcnt lgkmcnt(3)
	v_mfma_f32_32x32x16_f16 v[50:65], v[156:159], v[160:163], v[50:65]
	global_load_dwordx4 v[102:105], v138, s[16:17] offset:896
	s_waitcnt lgkmcnt(2)
	v_mfma_f32_32x32x16_f16 v[34:49], v[164:167], v[160:163], v[34:49]
	ds_read_b128 v[160:163], v144 offset:18528
	s_waitcnt vmcnt(8)
	ds_write_b128 v142, v[70:73] offset:36864
	s_waitcnt lgkmcnt(3)
	v_mfma_f32_32x32x16_f16 v[18:33], v[156:159], v[168:171], v[18:33]
	ds_read_b128 v[156:159], v145 offset:55392
	global_load_dwordx4 v[110:113], v139, s[16:17] offset:896
	v_mfma_f32_32x32x16_f16 v[2:17], v[164:167], v[168:171], v[2:17]
	ds_read_b128 v[164:167], v145 offset:60000
	ds_read_b128 v[168:171], v144 offset:23136
	s_waitcnt vmcnt(8)
	ds_write_b128 v142, v[78:81] offset:41472
	s_waitcnt lgkmcnt(3)
	v_mfma_f32_32x32x16_f16 v[50:65], v[156:159], v[160:163], v[50:65]
	global_load_dwordx4 v[118:121], v140, s[16:17] offset:896
	s_waitcnt lgkmcnt(2)
	v_mfma_f32_32x32x16_f16 v[34:49], v[164:167], v[160:163], v[34:49]
	s_waitcnt vmcnt(8)
	ds_write_b128 v142, v[86:89] offset:46080
	s_waitcnt lgkmcnt(2)
	v_mfma_f32_32x32x16_f16 v[18:33], v[156:159], v[168:171], v[18:33]
	global_load_dwordx4 v[126:129], v141, s[16:17] offset:896
	v_mfma_f32_32x32x16_f16 v[2:17], v[164:167], v[168:171], v[2:17]
	s_waitcnt vmcnt(8)
	ds_write_b128 v142, v[94:97] offset:50688
	s_setprio 0
	s_waitcnt lgkmcnt(0)
	s_barrier
	s_setprio 1
	ds_read_b128 v[156:159], v145 offset:36864
	ds_read_b128 v[160:163], v144
	ds_read_b128 v[164:167], v145 offset:41472
	ds_read_b128 v[168:171], v144 offset:4608
	s_waitcnt lgkmcnt(2)
	v_mfma_f32_32x32x16_f16 v[50:65], v[156:159], v[160:163], v[50:65]
	global_load_dwordx4 v[66:69], v134, s[14:15] offset:1024
	s_waitcnt lgkmcnt(1)
	v_mfma_f32_32x32x16_f16 v[34:49], v[164:167], v[160:163], v[34:49]
	ds_read_b128 v[160:163], v144 offset:32
	s_waitcnt vmcnt(8)
	ds_write_b128 v142, v[98:101] offset:18432
	s_waitcnt lgkmcnt(2)
	v_mfma_f32_32x32x16_f16 v[18:33], v[156:159], v[168:171], v[18:33]
	ds_read_b128 v[156:159], v145 offset:36896
	global_load_dwordx4 v[74:77], v135, s[14:15] offset:1024
	v_mfma_f32_32x32x16_f16 v[2:17], v[164:167], v[168:171], v[2:17]
	ds_read_b128 v[164:167], v145 offset:41504
	ds_read_b128 v[168:171], v144 offset:4640
	s_waitcnt vmcnt(8)
	ds_write_b128 v142, v[106:109] offset:23040
	s_waitcnt lgkmcnt(3)
	v_mfma_f32_32x32x16_f16 v[50:65], v[156:159], v[160:163], v[50:65]
	global_load_dwordx4 v[82:85], v136, s[14:15] offset:1024
	s_waitcnt lgkmcnt(2)
	v_mfma_f32_32x32x16_f16 v[34:49], v[164:167], v[160:163], v[34:49]
	ds_read_b128 v[160:163], v144 offset:64
	s_waitcnt vmcnt(8)
	ds_write_b128 v142, v[114:117] offset:27648
	s_waitcnt lgkmcnt(3)
	v_mfma_f32_32x32x16_f16 v[18:33], v[156:159], v[168:171], v[18:33]
	ds_read_b128 v[156:159], v145 offset:36928
	global_load_dwordx4 v[90:93], v137, s[14:15] offset:1024
	v_mfma_f32_32x32x16_f16 v[2:17], v[164:167], v[168:171], v[2:17]
	ds_read_b128 v[164:167], v145 offset:41536
	ds_read_b128 v[168:171], v144 offset:4672
	s_waitcnt vmcnt(8)
	ds_write_b128 v142, v[122:125] offset:32256
	s_waitcnt lgkmcnt(3)
	v_mfma_f32_32x32x16_f16 v[50:65], v[156:159], v[160:163], v[50:65]
	global_load_dwordx4 v[70:73], v138, s[16:17] offset:1024
	s_waitcnt lgkmcnt(2)
	v_mfma_f32_32x32x16_f16 v[34:49], v[164:167], v[160:163], v[34:49]
	ds_read_b128 v[160:163], v144 offset:96
	s_waitcnt vmcnt(8)
	ds_write_b128 v142, v[102:105] offset:55296
	s_waitcnt lgkmcnt(3)
	v_mfma_f32_32x32x16_f16 v[18:33], v[156:159], v[168:171], v[18:33]
	ds_read_b128 v[156:159], v145 offset:36960
	global_load_dwordx4 v[78:81], v139, s[16:17] offset:1024
	v_mfma_f32_32x32x16_f16 v[2:17], v[164:167], v[168:171], v[2:17]
	ds_read_b128 v[164:167], v145 offset:41568
	ds_read_b128 v[168:171], v144 offset:4704
	s_waitcnt vmcnt(8)
	ds_write_b128 v142, v[110:113] offset:59904
	s_waitcnt lgkmcnt(3)
	v_mfma_f32_32x32x16_f16 v[50:65], v[156:159], v[160:163], v[50:65]
	global_load_dwordx4 v[86:89], v140, s[16:17] offset:1024
	s_waitcnt lgkmcnt(2)
	v_mfma_f32_32x32x16_f16 v[34:49], v[164:167], v[160:163], v[34:49]
	s_waitcnt vmcnt(8)
	ds_write_b128 v142, v[118:121] offset:64512
	s_waitcnt lgkmcnt(2)
	v_mfma_f32_32x32x16_f16 v[18:33], v[156:159], v[168:171], v[18:33]
	global_load_dwordx4 v[94:97], v141, s[16:17] offset:1024
	v_mfma_f32_32x32x16_f16 v[2:17], v[164:167], v[168:171], v[2:17]
	s_waitcnt vmcnt(8)
	ds_write_b128 v143, v[126:129] offset:64512
	s_setprio 0
	s_waitcnt lgkmcnt(0)
	s_barrier
; #define GEMM_GLOAD(P, kt_) { GEMM_GL1(P, 0, kt_) GEMM_GL1(P, 1, kt_) GEMM_GL1(P, 2, kt_) GEMM_GL1(P, 3, kt_) }
; #define GEMM_LSTORE(P, buf_) { GEMM_LS1(P, 0, buf_) GEMM_LS1(P, 1, buf_) GEMM_LS1(P, 2, buf_) GEMM_LS1(P, 3, buf_) }
; template <bool DEEP>
; DI void gemm_mainloop_t(const u16* __restrict__ Ag, int lda, const u16* __restrict__ Bg, int ldb, int K, char* ldsraw,
;                         f32x16 (&acc)[2][2], int akstep) {
;     ...
;     for (int kt = 0; kt < nk; kt += 2) {
;       if (kt + 2 < nk) GEMM_GLOAD(x, kt + 2);
;       GEMM_COMPUTE(0);
;       GEMM_LSTORE(y, 1);
;       __syncthreads();
;       if (kt + 3 < nk) GEMM_GLOAD(y, kt + 3);
;       GEMM_COMPUTE(1);
;       if (kt + 2 < nk) GEMM_LSTORE(x, 0);
;       __syncthreads();
;     }
	s_setprio 1
	ds_read_b128 v[156:159], v145 offset:55296
	ds_read_b128 v[160:163], v144 offset:18432
	ds_read_b128 v[164:167], v145 offset:59904
	ds_read_b128 v[168:171], v144 offset:23040
	s_waitcnt lgkmcnt(2)
	v_mfma_f32_32x32x16_f16 v[50:65], v[156:159], v[160:163], v[50:65]
	global_load_dwordx4 v[98:101], v134, s[14:15] offset:1152
	s_waitcnt lgkmcnt(1)
	v_mfma_f32_32x32x16_f16 v[34:49], v[164:167], v[160:163], v[34:49]
	ds_read_b128 v[160:163], v144 offset:18464
	s_waitcnt vmcnt(8)
	ds_write_b128 v142, v[66:69]
	s_waitcnt lgkmcnt(2)
	v_mfma_f32_32x32x16_f16 v[18:33], v[156:159], v[168:171], v[18:33]
	ds_read_b128 v[156:159], v145 offset:55328
	global_load_dwordx4 v[106:109], v135, s[14:15] offset:1152
	v_mfma_f32_32x32x16_f16 v[2:17], v[164:167], v[168:171], v[2:17]
	ds_read_b128 v[164:167], v145 offset:59936
	ds_read_b128 v[168:171], v144 offset:23072
	s_waitcnt vmcnt(8)
	ds_write_b128 v142, v[74:77] offset:4608
	s_waitcnt lgkmcnt(3)
	v_mfma_f32_32x32x16_f16 v[50:65], v[156:159], v[160:163], v[50:65]
	global_load_dwordx4 v[114:117], v136, s[14:15] offset:1152
	s_waitcnt lgkmcnt(2)
	v_mfma_f32_32x32x16_f16 v[34:49], v[164:167], v[160:163], v[34:49]
	ds_read_b128 v[160:163], v144 offset:18496
	s_waitcnt vmcnt(8)
	ds_write_b128 v142, v[82:85] offset:9216
	s_waitcnt lgkmcnt(3)
	v_mfma_f32_32x32x16_f16 v[18:33], v[156:159], v[168:171], v[18:33]
	ds_read_b128 v[156:159], v145 offset:55360
	global_load_dwordx4 v[122:125], v137, s[14:15] offset:1152
	v_mfma_f32_32x32x16_f16 v[2:17], v[164:167], v[168:171], v[2:17]
	ds_read_b128 v[164:167], v145 offset:59968
	ds_read_b128 v[168:171], v144 offset:23104
	s_waitcnt vmcnt(8)
	ds_write_b128 v142, v[90:93] offset:13824
	s_waitcnt lgkmcnt(3)
	v_mfma_f32_32x32x16_f16 v[50:65], v[156:159], v[160:163], v[50:65]
	global_load_dwordx4 v[102:105], v138, s[16:17] offset:1152
	s_waitcnt lgkmcnt(2)
	v_mfma_f32_32x32x16_f16 v[34:49], v[164:167], v[160:163], v[34:49]
	ds_read_b128 v[160:163], v144 offset:18528
	s_waitcnt vmcnt(8)
	ds_write_b128 v142, v[70:73] offset:36864
	s_waitcnt lgkmcnt(3)
	v_mfma_f32_32x32x16_f16 v[18:33], v[156:159], v[168:171], v[18:33]
	ds_read_b128 v[156:159], v145 offset:55392
	global_load_dwordx4 v[110:113], v139, s[16:17] offset:1152
	v_mfma_f32_32x32x16_f16 v[2:17], v[164:167], v[168:171], v[2:17]
	ds_read_b128 v[164:167], v145 offset:60000
	ds_read_b128 v[168:171], v144 offset:23136
	s_waitcnt vmcnt(8)
	ds_write_b128 v142, v[78:81] offset:41472
	s_waitcnt lgkmcnt(3)
	v_mfma_f32_32x32x16_f16 v[50:65], v[156:159], v[160:163], v[50:65]
	global_load_dwordx4 v[118:121], v140, s[16:17] offset:1152
	s_waitcnt lgkmcnt(2)
	v_mfma_f32_32x32x16_f16 v[34:49], v[164:167], v[160:163], v[34:49]
	s_waitcnt vmcnt(8)
	ds_write_b128 v142, v[86:89] offset:46080
	s_waitcnt lgkmcnt(2)
	v_mfma_f32_32x32x16_f16 v[18:33], v[156:159], v[168:171], v[18:33]
	global_load_dwordx4 v[126:129], v141, s[16:17] offset:1152
	v_mfma_f32_32x32x16_f16 v[2:17], v[164:167], v[168:171], v[2:17]
	s_waitcnt vmcnt(8)
	ds_write_b128 v142, v[94:97] offset:50688
	s_setprio 0
	s_waitcnt lgkmcnt(0)
	s_barrier
	s_setprio 1
	ds_read_b128 v[156:159], v145 offset:36864
	ds_read_b128 v[160:163], v144
	ds_read_b128 v[164:167], v145 offset:41472
	ds_read_b128 v[168:171], v144 offset:4608
	s_waitcnt lgkmcnt(2)
	v_mfma_f32_32x32x16_f16 v[50:65], v[156:159], v[160:163], v[50:65]
	global_load_dwordx4 v[66:69], v134, s[14:15] offset:1280
	s_waitcnt lgkmcnt(1)
	v_mfma_f32_32x32x16_f16 v[34:49], v[164:167], v[160:163], v[34:49]
	ds_read_b128 v[160:163], v144 offset:32
	s_waitcnt vmcnt(8)
	ds_write_b128 v142, v[98:101] offset:18432
	s_waitcnt lgkmcnt(2)
	v_mfma_f32_32x32x16_f16 v[18:33], v[156:159], v[168:171], v[18:33]
	ds_read_b128 v[156:159], v145 offset:36896
	global_load_dwordx4 v[74:77], v135, s[14:15] offset:1280
	v_mfma_f32_32x32x16_f16 v[2:17], v[164:167], v[168:171], v[2:17]
	ds_read_b128 v[164:167], v145 offset:41504
	ds_read_b128 v[168:171], v144 offset:4640
	s_waitcnt vmcnt(8)
	ds_write_b128 v142, v[106:109] offset:23040
	s_waitcnt lgkmcnt(3)
	v_mfma_f32_32x32x16_f16 v[50:65], v[156:159], v[160:163], v[50:65]
	global_load_dwordx4 v[82:85], v136, s[14:15] offset:1280
	s_waitcnt lgkmcnt(2)
	v_mfma_f32_32x32x16_f16 v[34:49], v[164:167], v[160:163], v[34:49]
	ds_read_b128 v[160:163], v144 offset:64
	s_waitcnt vmcnt(8)
	ds_write_b128 v142, v[114:117] offset:27648
	s_waitcnt lgkmcnt(3)
	v_mfma_f32_32x32x16_f16 v[18:33], v[156:159], v[168:171], v[18:33]
	ds_read_b128 v[156:159], v145 offset:36928
	global_load_dwordx4 v[90:93], v137, s[14:15] offset:1280
	v_mfma_f32_32x32x16_f16 v[2:17], v[164:167], v[168:171], v[2:17]
	ds_read_b128 v[164:167], v145 offset:41536
	ds_read_b128 v[168:171], v144 offset:4672
	s_waitcnt vmcnt(8)
	ds_write_b128 v142, v[122:125] offset:32256
	s_waitcnt lgkmcnt(3)
	v_mfma_f32_32x32x16_f16 v[50:65], v[156:159], v[160:163], v[50:65]
	global_load_dwordx4 v[70:73], v138, s[16:17] offset:1280
	s_waitcnt lgkmcnt(2)
	v_mfma_f32_32x32x16_f16 v[34:49], v[164:167], v[160:163], v[34:49]
	ds_read_b128 v[160:163], v144 offset:96
	s_waitcnt vmcnt(8)
	ds_write_b128 v142, v[102:105] offset:55296
	s_waitcnt lgkmcnt(3)
	v_mfma_f32_32x32x16_f16 v[18:33], v[156:159], v[168:171], v[18:33]
	ds_read_b128 v[156:159], v145 offset:36960
	global_load_dwordx4 v[78:81], v139, s[16:17] offset:1280
	v_mfma_f32_32x32x16_f16 v[2:17], v[164:167], v[168:171], v[2:17]
	ds_read_b128 v[164:167], v145 offset:41568
	ds_read_b128 v[168:171], v144 offset:4704
	s_waitcnt vmcnt(8)
	ds_write_b128 v142, v[110:113] offset:59904
	s_waitcnt lgkmcnt(3)
	v_mfma_f32_32x32x16_f16 v[50:65], v[156:159], v[160:163], v[50:65]
	global_load_dwordx4 v[86:89], v140, s[16:17] offset:1280
	s_waitcnt lgkmcnt(2)
	v_mfma_f32_32x32x16_f16 v[34:49], v[164:167], v[160:163], v[34:49]
	s_waitcnt vmcnt(8)
	ds_write_b128 v142, v[118:121] offset:64512
	s_waitcnt lgkmcnt(2)
	v_mfma_f32_32x32x16_f16 v[18:33], v[156:159], v[168:171], v[18:33]
	global_load_dwordx4 v[94:97], v141, s[16:17] offset:1280
	v_mfma_f32_32x32x16_f16 v[2:17], v[164:167], v[168:171], v[2:17]
	s_waitcnt vmcnt(8)
	ds_write_b128 v143, v[126:129] offset:64512
	s_setprio 0
	s_waitcnt lgkmcnt(0)
	s_barrier
; #define GEMM_GLOAD(P, kt_) { GEMM_GL1(P, 0, kt_) GEMM_GL1(P, 1, kt_) GEMM_GL1(P, 2, kt_) GEMM_GL1(P, 3, kt_) }
; #define GEMM_LSTORE(P, buf_) { GEMM_LS1(P, 0, buf_) GEMM_LS1(P, 1, buf_) GEMM_LS1(P, 2, buf_) GEMM_LS1(P, 3, buf_) }
; template <bool DEEP>
; DI void gemm_mainloop_t(const u16* __restrict__ Ag, int lda, const u16* __restrict__ Bg, int ldb, int K, char* ldsraw,
;                         f32x16 (&acc)[2][2], int akstep) {
;     ...
;     for (int kt = 0; kt < nk; kt += 2) {
;       if (kt + 2 < nk) GEMM_GLOAD(x, kt + 2);
;       GEMM_COMPUTE(0);
;       GEMM_LSTORE(y, 1);
;       __syncthreads();
;       if (kt + 3 < nk) GEMM_GLOAD(y, kt + 3);
;       GEMM_COMPUTE(1);
;       if (kt + 2 < nk) GEMM_LSTORE(x, 0);
;       __syncthreads();
;     }
	s_setprio 1
	ds_read_b128 v[156:159], v145 offset:55296
	ds_read_b128 v[160:163], v144 offset:18432
	ds_read_b128 v[164:167], v145 offset:59904
	ds_read_b128 v[168:171], v144 offset:23040
	s_waitcnt lgkmcnt(2)
	v_mfma_f32_32x32x16_f16 v[50:65], v[156:159], v[160:163], v[50:65]
	global_load_dwordx4 v[98:101], v134, s[14:15] offset:1408
	s_waitcnt lgkmcnt(1)
	v_mfma_f32_32x32x16_f16 v[34:49], v[164:167], v[160:163], v[34:49]
	ds_read_b128 v[160:163], v144 offset:18464
	s_waitcnt vmcnt(8)
	ds_write_b128 v142, v[66:69]
	s_waitcnt lgkmcnt(2)
	v_mfma_f32_32x32x16_f16 v[18:33], v[156:159], v[168:171], v[18:33]
	ds_read_b128 v[156:159], v145 offset:55328
	global_load_dwordx4 v[106:109], v135, s[14:15] offset:1408
	v_mfma_f32_32x32x16_f16 v[2:17], v[164:167], v[168:171], v[2:17]
	ds_read_b128 v[164:167], v145 offset:59936
	ds_read_b128 v[168:171], v144 offset:23072
	s_waitcnt vmcnt(8)
	ds_write_b128 v142, v[74:77] offset:4608
	s_waitcnt lgkmcnt(3)
	v_mfma_f32_32x32x16_f16 v[50:65], v[156:159], v[160:163], v[50:65]
	global_load_dwordx4 v[114:117], v136, s[14:15] offset:1408
	s_waitcnt lgkmcnt(2)
	v_mfma_f32_32x32x16_f16 v[34:49], v[164:167], v[160:163], v[34:49]
	ds_read_b128 v[160:163], v144 offset:18496
	s_waitcnt vmcnt(8)
	ds_write_b128 v142, v[82:85] offset:9216
	s_waitcnt lgkmcnt(3)
	v_mfma_f32_32x32x16_f16 v[18:33], v[156:159], v[168:171], v[18:33]
	ds_read_b128 v[156:159], v145 offset:55360
	global_load_dwordx4 v[122:125], v137, s[14:15] offset:1408
	v_mfma_f32_32x32x16_f16 v[2:17], v[164:167], v[168:171], v[2:17]
	ds_read_b128 v[164:167], v145 offset:59968
	ds_read_b128 v[168:171], v144 offset:23104
	s_waitcnt vmcnt(8)
	ds_write_b128 v142, v[90:93] offset:13824
	s_waitcnt lgkmcnt(3)
	v_mfma_f32_32x32x16_f16 v[50:65], v[156:159], v[160:163], v[50:65]
	global_load_dwordx4 v[102:105], v138, s[16:17] offset:1408
	s_waitcnt lgkmcnt(2)
	v_mfma_f32_32x32x16_f16 v[34:49], v[164:167], v[160:163], v[34:49]
	ds_read_b128 v[160:163], v144 offset:18528
	s_waitcnt vmcnt(8)
	ds_write_b128 v142, v[70:73] offset:36864
	s_waitcnt lgkmcnt(3)
	v_mfma_f32_32x32x16_f16 v[18:33], v[156:159], v[168:171], v[18:33]
	ds_read_b128 v[156:159], v145 offset:55392
	global_load_dwordx4 v[110:113], v139, s[16:17] offset:1408
	v_mfma_f32_32x32x16_f16 v[2:17], v[164:167], v[168:171], v[2:17]
	ds_read_b128 v[164:167], v145 offset:60000
	ds_read_b128 v[168:171], v144 offset:23136
	s_waitcnt vmcnt(8)
	ds_write_b128 v142, v[78:81] offset:41472
	s_waitcnt lgkmcnt(3)
	v_mfma_f32_32x32x16_f16 v[50:65], v[156:159], v[160:163], v[50:65]
	global_load_dwordx4 v[118:121], v140, s[16:17] offset:1408
	s_waitcnt lgkmcnt(2)
	v_mfma_f32_32x32x16_f16 v[34:49], v[164:167], v[160:163], v[34:49]
	s_waitcnt vmcnt(8)
	ds_write_b128 v142, v[86:89] offset:46080
	s_waitcnt lgkmcnt(2)
	v_mfma_f32_32x32x16_f16 v[18:33], v[156:159], v[168:171], v[18:33]
	global_load_dwordx4 v[126:129], v141, s[16:17] offset:1408
	v_mfma_f32_32x32x16_f16 v[2:17], v[164:167], v[168:171], v[2:17]
	s_waitcnt vmcnt(8)
	ds_write_b128 v142, v[94:97] offset:50688
	s_setprio 0
	s_waitcnt lgkmcnt(0)
	s_barrier
	s_setprio 1
	ds_read_b128 v[156:159], v145 offset:36864
	ds_read_b128 v[160:163], v144
	ds_read_b128 v[164:167], v145 offset:41472
	ds_read_b128 v[168:171], v144 offset:4608
	s_waitcnt lgkmcnt(2)
	v_mfma_f32_32x32x16_f16 v[50:65], v[156:159], v[160:163], v[50:65]
	global_load_dwordx4 v[66:69], v134, s[14:15] offset:1536
	s_waitcnt lgkmcnt(1)
	v_mfma_f32_32x32x16_f16 v[34:49], v[164:167], v[160:163], v[34:49]
	ds_read_b128 v[160:163], v144 offset:32
	s_waitcnt vmcnt(8)
	ds_write_b128 v142, v[98:101] offset:18432
	s_waitcnt lgkmcnt(2)
	v_mfma_f32_32x32x16_f16 v[18:33], v[156:159], v[168:171], v[18:33]
	ds_read_b128 v[156:159], v145 offset:36896
	global_load_dwordx4 v[74:77], v135, s[14:15] offset:1536
	v_mfma_f32_32x32x16_f16 v[2:17], v[164:167], v[168:171], v[2:17]
	ds_read_b128 v[164:167], v145 offset:41504
	ds_read_b128 v[168:171], v144 offset:4640
	s_waitcnt vmcnt(8)
	ds_write_b128 v142, v[106:109] offset:23040
	s_waitcnt lgkmcnt(3)
	v_mfma_f32_32x32x16_f16 v[50:65], v[156:159], v[160:163], v[50:65]
	global_load_dwordx4 v[82:85], v136, s[14:15] offset:1536
	s_waitcnt lgkmcnt(2)
	v_mfma_f32_32x32x16_f16 v[34:49], v[164:167], v[160:163], v[34:49]
	ds_read_b128 v[160:163], v144 offset:64
	s_waitcnt vmcnt(8)
	ds_write_b128 v142, v[114:117] offset:27648
	s_waitcnt lgkmcnt(3)
	v_mfma_f32_32x32x16_f16 v[18:33], v[156:159], v[168:171], v[18:33]
	ds_read_b128 v[156:159], v145 offset:36928
	global_load_dwordx4 v[90:93], v137, s[14:15] offset:1536
	v_mfma_f32_32x32x16_f16 v[2:17], v[164:167], v[168:171], v[2:17]
	ds_read_b128 v[164:167], v145 offset:41536
	ds_read_b128 v[168:171], v144 offset:4672
	s_waitcnt vmcnt(8)
	ds_write_b128 v142, v[122:125] offset:32256
	s_waitcnt lgkmcnt(3)
	v_mfma_f32_32x32x16_f16 v[50:65], v[156:159], v[160:163], v[50:65]
	global_load_dwordx4 v[70:73], v138, s[16:17] offset:1536
	s_waitcnt lgkmcnt(2)
	v_mfma_f32_32x32x16_f16 v[34:49], v[164:167], v[160:163], v[34:49]
	ds_read_b128 v[160:163], v144 offset:96
	s_waitcnt vmcnt(8)
	ds_write_b128 v142, v[102:105] offset:55296
	s_waitcnt lgkmcnt(3)
	v_mfma_f32_32x32x16_f16 v[18:33], v[156:159], v[168:171], v[18:33]
	ds_read_b128 v[156:159], v145 offset:36960
	global_load_dwordx4 v[78:81], v139, s[16:17] offset:1536
	v_mfma_f32_32x32x16_f16 v[2:17], v[164:167], v[168:171], v[2:17]
	ds_read_b128 v[164:167], v145 offset:41568
	ds_read_b128 v[168:171], v144 offset:4704
	s_waitcnt vmcnt(8)
	ds_write_b128 v142, v[110:113] offset:59904
	s_waitcnt lgkmcnt(3)
	v_mfma_f32_32x32x16_f16 v[50:65], v[156:159], v[160:163], v[50:65]
	global_load_dwordx4 v[86:89], v140, s[16:17] offset:1536
	s_waitcnt lgkmcnt(2)
	v_mfma_f32_32x32x16_f16 v[34:49], v[164:167], v[160:163], v[34:49]
	s_waitcnt vmcnt(8)
	ds_write_b128 v142, v[118:121] offset:64512
	s_waitcnt lgkmcnt(2)
	v_mfma_f32_32x32x16_f16 v[18:33], v[156:159], v[168:171], v[18:33]
	global_load_dwordx4 v[94:97], v141, s[16:17] offset:1536
	v_mfma_f32_32x32x16_f16 v[2:17], v[164:167], v[168:171], v[2:17]
	s_waitcnt vmcnt(8)
	ds_write_b128 v143, v[126:129] offset:64512
	s_setprio 0
	s_waitcnt lgkmcnt(0)
	s_barrier
; #define GEMM_GLOAD(P, kt_) { GEMM_GL1(P, 0, kt_) GEMM_GL1(P, 1, kt_) GEMM_GL1(P, 2, kt_) GEMM_GL1(P, 3, kt_) }
; #define GEMM_LSTORE(P, buf_) { GEMM_LS1(P, 0, buf_) GEMM_LS1(P, 1, buf_) GEMM_LS1(P, 2, buf_) GEMM_LS1(P, 3, buf_) }
; template <bool DEEP>
; DI void gemm_mainloop_t(const u16* __restrict__ Ag, int lda, const u16* __restrict__ Bg, int ldb, int K, char* ldsraw,
;                         f32x16 (&acc)[2][2], int akstep) {
;     ...
;     for (int kt = 0; kt < nk; kt += 2) {
;       if (kt + 2 < nk) GEMM_GLOAD(x, kt + 2);
;       GEMM_COMPUTE(0);
;       GEMM_LSTORE(y, 1);
;       __syncthreads();
;       if (kt + 3 < nk) GEMM_GLOAD(y, kt + 3);
;       GEMM_COMPUTE(1);
;       if (kt + 2 < nk) GEMM_LSTORE(x, 0);
;       __syncthreads();
;     }
	s_setprio 1
	ds_read_b128 v[156:159], v145 offset:55296
	ds_read_b128 v[160:163], v144 offset:18432
	ds_read_b128 v[164:167], v145 offset:59904
	ds_read_b128 v[168:171], v144 offset:23040
	s_waitcnt lgkmcnt(2)
	v_mfma_f32_32x32x16_f16 v[50:65], v[156:159], v[160:163], v[50:65]
	global_load_dwordx4 v[98:101], v134, s[14:15] offset:1664
	s_waitcnt lgkmcnt(1)
	v_mfma_f32_32x32x16_f16 v[34:49], v[164:167], v[160:163], v[34:49]
	ds_read_b128 v[160:163], v144 offset:18464
	s_waitcnt vmcnt(8)
	ds_write_b128 v142, v[66:69]
	s_waitcnt lgkmcnt(2)
	v_mfma_f32_32x32x16_f16 v[18:33], v[156:159], v[168:171], v[18:33]
	ds_read_b128 v[156:159], v145 offset:55328
	global_load_dwordx4 v[106:109], v135, s[14:15] offset:1664
	v_mfma_f32_32x32x16_f16 v[2:17], v[164:167], v[168:171], v[2:17]
	ds_read_b128 v[164:167], v145 offset:59936
	ds_read_b128 v[168:171], v144 offset:23072
	s_waitcnt vmcnt(8)
	ds_write_b128 v142, v[74:77] offset:4608
	s_waitcnt lgkmcnt(3)
	v_mfma_f32_32x32x16_f16 v[50:65], v[156:159], v[160:163], v[50:65]
	global_load_dwordx4 v[114:117], v136, s[14:15] offset:1664
	s_waitcnt lgkmcnt(2)
	v_mfma_f32_32x32x16_f16 v[34:49], v[164:167], v[160:163], v[34:49]
	ds_read_b128 v[160:163], v144 offset:18496
	s_waitcnt vmcnt(8)
	ds_write_b128 v142, v[82:85] offset:9216
	s_waitcnt lgkmcnt(3)
	v_mfma_f32_32x32x16_f16 v[18:33], v[156:159], v[168:171], v[18:33]
	ds_read_b128 v[156:159], v145 offset:55360
	global_load_dwordx4 v[122:125], v137, s[14:15] offset:1664
	v_mfma_f32_32x32x16_f16 v[2:17], v[164:167], v[168:171], v[2:17]
	ds_read_b128 v[164:167], v145 offset:59968
	ds_read_b128 v[168:171], v144 offset:23104
	s_waitcnt vmcnt(8)
	ds_write_b128 v142, v[90:93] offset:13824
	s_waitcnt lgkmcnt(3)
	v_mfma_f32_32x32x16_f16 v[50:65], v[156:159], v[160:163], v[50:65]
	global_load_dwordx4 v[102:105], v138, s[16:17] offset:1664
	s_waitcnt lgkmcnt(2)
	v_mfma_f32_32x32x16_f16 v[34:49], v[164:167], v[160:163], v[34:49]
	ds_read_b128 v[160:163], v144 offset:18528
	s_waitcnt vmcnt(8)
	ds_write_b128 v142, v[70:73] offset:36864
	s_waitcnt lgkmcnt(3)
	v_mfma_f32_32x32x16_f16 v[18:33], v[156:159], v[168:171], v[18:33]
	ds_read_b128 v[156:159], v145 offset:55392
	global_load_dwordx4 v[110:113], v139, s[16:17] offset:1664
	v_mfma_f32_32x32x16_f16 v[2:17], v[164:167], v[168:171], v[2:17]
	ds_read_b128 v[164:167], v145 offset:60000
	ds_read_b128 v[168:171], v144 offset:23136
	s_waitcnt vmcnt(8)
	ds_write_b128 v142, v[78:81] offset:41472
	s_waitcnt lgkmcnt(3)
	v_mfma_f32_32x32x16_f16 v[50:65], v[156:159], v[160:163], v[50:65]
	global_load_dwordx4 v[118:121], v140, s[16:17] offset:1664
	s_waitcnt lgkmcnt(2)
	v_mfma_f32_32x32x16_f16 v[34:49], v[164:167], v[160:163], v[34:49]
	s_waitcnt vmcnt(8)
	ds_write_b128 v142, v[86:89] offset:46080
	s_waitcnt lgkmcnt(2)
	v_mfma_f32_32x32x16_f16 v[18:33], v[156:159], v[168:171], v[18:33]
	global_load_dwordx4 v[126:129], v141, s[16:17] offset:1664
	v_mfma_f32_32x32x16_f16 v[2:17], v[164:167], v[168:171], v[2:17]
	s_waitcnt vmcnt(8)
	ds_write_b128 v142, v[94:97] offset:50688
	s_setprio 0
	s_waitcnt lgkmcnt(0)
	s_barrier
	s_setprio 1
	ds_read_b128 v[156:159], v145 offset:36864
	ds_read_b128 v[160:163], v144
	ds_read_b128 v[164:167], v145 offset:41472
	ds_read_b128 v[168:171], v144 offset:4608
	s_waitcnt lgkmcnt(2)
	v_mfma_f32_32x32x16_f16 v[50:65], v[156:159], v[160:163], v[50:65]
	global_load_dwordx4 v[66:69], v134, s[14:15] offset:1792
	s_waitcnt lgkmcnt(1)
	v_mfma_f32_32x32x16_f16 v[34:49], v[164:167], v[160:163], v[34:49]
	ds_read_b128 v[160:163], v144 offset:32
	s_waitcnt vmcnt(8)
	ds_write_b128 v142, v[98:101] offset:18432
	s_waitcnt lgkmcnt(2)
	v_mfma_f32_32x32x16_f16 v[18:33], v[156:159], v[168:171], v[18:33]
	ds_read_b128 v[156:159], v145 offset:36896
	global_load_dwordx4 v[74:77], v135, s[14:15] offset:1792
	v_mfma_f32_32x32x16_f16 v[2:17], v[164:167], v[168:171], v[2:17]
	ds_read_b128 v[164:167], v145 offset:41504
	ds_read_b128 v[168:171], v144 offset:4640
	s_waitcnt vmcnt(8)
	ds_write_b128 v142, v[106:109] offset:23040
	s_waitcnt lgkmcnt(3)
	v_mfma_f32_32x32x16_f16 v[50:65], v[156:159], v[160:163], v[50:65]
	global_load_dwordx4 v[82:85], v136, s[14:15] offset:1792
	s_waitcnt lgkmcnt(2)
	v_mfma_f32_32x32x16_f16 v[34:49], v[164:167], v[160:163], v[34:49]
	ds_read_b128 v[160:163], v144 offset:64
	s_waitcnt vmcnt(8)
	ds_write_b128 v142, v[114:117] offset:27648
	s_waitcnt lgkmcnt(3)
	v_mfma_f32_32x32x16_f16 v[18:33], v[156:159], v[168:171], v[18:33]
	ds_read_b128 v[156:159], v145 offset:36928
	global_load_dwordx4 v[90:93], v137, s[14:15] offset:1792
	v_mfma_f32_32x32x16_f16 v[2:17], v[164:167], v[168:171], v[2:17]
	ds_read_b128 v[164:167], v145 offset:41536
	ds_read_b128 v[168:171], v144 offset:4672
	s_waitcnt vmcnt(8)
	ds_write_b128 v142, v[122:125] offset:32256
	s_waitcnt lgkmcnt(3)
	v_mfma_f32_32x32x16_f16 v[50:65], v[156:159], v[160:163], v[50:65]
	global_load_dwordx4 v[70:73], v138, s[16:17] offset:1792
	s_waitcnt lgkmcnt(2)
	v_mfma_f32_32x32x16_f16 v[34:49], v[164:167], v[160:163], v[34:49]
	ds_read_b128 v[160:163], v144 offset:96
	s_waitcnt vmcnt(8)
	ds_write_b128 v142, v[102:105] offset:55296
	s_waitcnt lgkmcnt(3)
	v_mfma_f32_32x32x16_f16 v[18:33], v[156:159], v[168:171], v[18:33]
	ds_read_b128 v[156:159], v145 offset:36960
	global_load_dwordx4 v[78:81], v139, s[16:17] offset:1792
	v_mfma_f32_32x32x16_f16 v[2:17], v[164:167], v[168:171], v[2:17]
	ds_read_b128 v[164:167], v145 offset:41568
	ds_read_b128 v[168:171], v144 offset:4704
	s_waitcnt vmcnt(8)
	ds_write_b128 v142, v[110:113] offset:59904
	s_waitcnt lgkmcnt(3)
	v_mfma_f32_32x32x16_f16 v[50:65], v[156:159], v[160:163], v[50:65]
	global_load_dwordx4 v[86:89], v140, s[16:17] offset:1792
	s_waitcnt lgkmcnt(2)
	v_mfma_f32_32x32x16_f16 v[34:49], v[164:167], v[160:163], v[34:49]
	s_waitcnt vmcnt(8)
	ds_write_b128 v142, v[118:121] offset:64512
	s_waitcnt lgkmcnt(2)
	v_mfma_f32_32x32x16_f16 v[18:33], v[156:159], v[168:171], v[18:33]
	global_load_dwordx4 v[94:97], v141, s[16:17] offset:1792
	v_mfma_f32_32x32x16_f16 v[2:17], v[164:167], v[168:171], v[2:17]
	s_waitcnt vmcnt(8)
	ds_write_b128 v143, v[126:129] offset:64512
	s_setprio 0
	s_waitcnt lgkmcnt(0)
	s_barrier
; #define GEMM_GLOAD(P, kt_) { GEMM_GL1(P, 0, kt_) GEMM_GL1(P, 1, kt_) GEMM_GL1(P, 2, kt_) GEMM_GL1(P, 3, kt_) }
; #define GEMM_LSTORE(P, buf_) { GEMM_LS1(P, 0, buf_) GEMM_LS1(P, 1, buf_) GEMM_LS1(P, 2, buf_) GEMM_LS1(P, 3, buf_) }
; template <bool DEEP>
; DI void gemm_mainloop_t(const u16* __restrict__ Ag, int lda, const u16* __restrict__ Bg, int ldb, int K, char* ldsraw,
;                         f32x16 (&acc)[2][2], int akstep) {
;     ...
;     for (int kt = 0; kt < nk; kt += 2) {
;       if (kt + 2 < nk) GEMM_GLOAD(x, kt + 2);
;       GEMM_COMPUTE(0);
;       GEMM_LSTORE(y, 1);
;       __syncthreads();
;       if (kt + 3 < nk) GEMM_GLOAD(y, kt + 3);
;       GEMM_COMPUTE(1);
;       if (kt + 2 < nk) GEMM_LSTORE(x, 0);
;       __syncthreads();
;     }
	s_setprio 1
	ds_read_b128 v[156:159], v145 offset:55296
	ds_read_b128 v[160:163], v144 offset:18432
	ds_read_b128 v[164:167], v145 offset:59904
	ds_read_b128 v[168:171], v144 offset:23040
	s_waitcnt lgkmcnt(2)
	v_mfma_f32_32x32x16_f16 v[50:65], v[156:159], v[160:163], v[50:65]
	global_load_dwordx4 v[98:101], v134, s[14:15] offset:1920
	s_waitcnt lgkmcnt(1)
	v_mfma_f32_32x32x16_f16 v[34:49], v[164:167], v[160:163], v[34:49]
	ds_read_b128 v[160:163], v144 offset:18464
	s_waitcnt vmcnt(8)
	ds_write_b128 v142, v[66:69]
	s_waitcnt lgkmcnt(2)
	v_mfma_f32_32x32x16_f16 v[18:33], v[156:159], v[168:171], v[18:33]
	ds_read_b128 v[156:159], v145 offset:55328
	global_load_dwordx4 v[106:109], v135, s[14:15] offset:1920
	v_mfma_f32_32x32x16_f16 v[2:17], v[164:167], v[168:171], v[2:17]
	ds_read_b128 v[164:167], v145 offset:59936
	ds_read_b128 v[168:171], v144 offset:23072
	s_waitcnt vmcnt(8)
	ds_write_b128 v142, v[74:77] offset:4608
	s_waitcnt lgkmcnt(3)
	v_mfma_f32_32x32x16_f16 v[50:65], v[156:159], v[160:163], v[50:65]
	global_load_dwordx4 v[114:117], v136, s[14:15] offset:1920
	s_waitcnt lgkmcnt(2)
	v_mfma_f32_32x32x16_f16 v[34:49], v[164:167], v[160:163], v[34:49]
	ds_read_b128 v[160:163], v144 offset:18496
	s_waitcnt vmcnt(8)
	ds_write_b128 v142, v[82:85] offset:9216
	s_waitcnt lgkmcnt(3)
	v_mfma_f32_32x32x16_f16 v[18:33], v[156:159], v[168:171], v[18:33]
	ds_read_b128 v[156:159], v145 offset:55360
	global_load_dwordx4 v[122:125], v137, s[14:15] offset:1920
	v_mfma_f32_32x32x16_f16 v[2:17], v[164:167], v[168:171], v[2:17]
	ds_read_b128 v[164:167], v145 offset:59968
	ds_read_b128 v[168:171], v144 offset:23104
	s_waitcnt vmcnt(8)
	ds_write_b128 v142, v[90:93] offset:13824
	s_waitcnt lgkmcnt(3)
	v_mfma_f32_32x32x16_f16 v[50:65], v[156:159], v[160:163], v[50:65]
	global_load_dwordx4 v[102:105], v138, s[16:17] offset:1920
	s_waitcnt lgkmcnt(2)
	v_mfma_f32_32x32x16_f16 v[34:49], v[164:167], v[160:163], v[34:49]
	ds_read_b128 v[160:163], v144 offset:18528
	s_waitcnt vmcnt(8)
	ds_write_b128 v142, v[70:73] offset:36864
	s_waitcnt lgkmcnt(3)
	v_mfma_f32_32x32x16_f16 v[18:33], v[156:159], v[168:171], v[18:33]
	ds_read_b128 v[156:159], v145 offset:55392
	global_load_dwordx4 v[110:113], v139, s[16:17] offset:1920
	v_mfma_f32_32x32x16_f16 v[2:17], v[164:167], v[168:171], v[2:17]
	ds_read_b128 v[164:167], v145 offset:60000
	ds_read_b128 v[168:171], v144 offset:23136
	s_waitcnt vmcnt(8)
	ds_write_b128 v142, v[78:81] offset:41472
	s_waitcnt lgkmcnt(3)
	v_mfma_f32_32x32x16_f16 v[50:65], v[156:159], v[160:163], v[50:65]
	global_load_dwordx4 v[118:121], v140, s[16:17] offset:1920
	s_waitcnt lgkmcnt(2)
	v_mfma_f32_32x32x16_f16 v[34:49], v[164:167], v[160:163], v[34:49]
	s_waitcnt vmcnt(8)
	ds_write_b128 v142, v[86:89] offset:46080
	s_waitcnt lgkmcnt(2)
	v_mfma_f32_32x32x16_f16 v[18:33], v[156:159], v[168:171], v[18:33]
	global_load_dwordx4 v[126:129], v141, s[16:17] offset:1920
	v_mfma_f32_32x32x16_f16 v[2:17], v[164:167], v[168:171], v[2:17]
	s_waitcnt vmcnt(8)
	ds_write_b128 v142, v[94:97] offset:50688
	s_setprio 0
	s_waitcnt lgkmcnt(0)
	s_barrier
; #define GEMM_GLOAD(P, kt_) { GEMM_GL1(P, 0, kt_) GEMM_GL1(P, 1, kt_) GEMM_GL1(P, 2, kt_) GEMM_GL1(P, 3, kt_) }
; #define GEMM_LSTORE(P, buf_) { GEMM_LS1(P, 0, buf_) GEMM_LS1(P, 1, buf_) GEMM_LS1(P, 2, buf_) GEMM_LS1(P, 3, buf_) }
; template <bool DEEP>
; DI void gemm_mainloop_t(const u16* __restrict__ Ag, int lda, const u16* __restrict__ Bg, int ldb, int K, char* ldsraw,
;                         f32x16 (&acc)[2][2], int akstep) {
;     ...
;     for (int kt = 0; kt < nk; kt += 2) {
;       if (kt + 2 < nk) GEMM_GLOAD(x, kt + 2);
;       GEMM_COMPUTE(0);
;       GEMM_LSTORE(y, 1);
;       __syncthreads();
;       if (kt + 3 < nk) GEMM_GLOAD(y, kt + 3);
;       GEMM_COMPUTE(1);
;       if (kt + 2 < nk) GEMM_LSTORE(x, 0);
;       __syncthreads();
;     }
; DI void phase1(const Params& p, int l, char* lds) {
;     ...
;     {
;       const int col0 = nt * 128 + wn * 64;
;       const float* gain = nullptr;
;       float sc = 1.f;
;       if (col0 < 512) { gain = p.qn_a + l * 64; sc = QSCALE; }
;       else if (col0 < 1024) { gain = p.kn_a + l * 64; }
;       else if (col0 >= QC && col0 < QC + 512) { gain = p.qn_c + l * 64; sc = QSCALE; }
;       else if ((col0 >= KSC && col0 < KSC + 128) || (col0 >= KWC && col0 < KWC + 128)) { gain = p.kn_c + l * 64; }
;       if (gain != nullptr) {
	s_setprio 1
	ds_read_b128 v[156:159], v145 offset:36864
	ds_read_b128 v[160:163], v144
	ds_read_b128 v[164:167], v145 offset:41472
	ds_read_b128 v[168:171], v144 offset:4608
	s_waitcnt lgkmcnt(2)
	v_mfma_f32_32x32x16_f16 v[50:65], v[156:159], v[160:163], v[50:65]
	s_waitcnt lgkmcnt(1)
	v_mfma_f32_32x32x16_f16 v[34:49], v[164:167], v[160:163], v[34:49]
	ds_read_b128 v[160:163], v144 offset:32
	s_waitcnt vmcnt(7)
	ds_write_b128 v142, v[98:101] offset:18432
	s_waitcnt lgkmcnt(2)
	v_mfma_f32_32x32x16_f16 v[18:33], v[156:159], v[168:171], v[18:33]
	ds_read_b128 v[156:159], v145 offset:36896
	v_mfma_f32_32x32x16_f16 v[2:17], v[164:167], v[168:171], v[2:17]
	ds_read_b128 v[164:167], v145 offset:41504
	ds_read_b128 v[168:171], v144 offset:4640
	s_waitcnt vmcnt(6)
	ds_write_b128 v142, v[106:109] offset:23040
	s_waitcnt lgkmcnt(3)
	v_mfma_f32_32x32x16_f16 v[50:65], v[156:159], v[160:163], v[50:65]
	s_waitcnt lgkmcnt(2)
	v_mfma_f32_32x32x16_f16 v[34:49], v[164:167], v[160:163], v[34:49]
	ds_read_b128 v[160:163], v144 offset:64
	s_waitcnt vmcnt(5)
	ds_write_b128 v142, v[114:117] offset:27648
	s_waitcnt lgkmcnt(3)
	v_mfma_f32_32x32x16_f16 v[18:33], v[156:159], v[168:171], v[18:33]
	ds_read_b128 v[156:159], v145 offset:36928
	v_mfma_f32_32x32x16_f16 v[2:17], v[164:167], v[168:171], v[2:17]
	ds_read_b128 v[164:167], v145 offset:41536
	ds_read_b128 v[168:171], v144 offset:4672
	s_waitcnt vmcnt(4)
	ds_write_b128 v142, v[122:125] offset:32256
	s_waitcnt lgkmcnt(3)
	v_mfma_f32_32x32x16_f16 v[50:65], v[156:159], v[160:163], v[50:65]
	s_waitcnt lgkmcnt(2)
	v_mfma_f32_32x32x16_f16 v[34:49], v[164:167], v[160:163], v[34:49]
	ds_read_b128 v[160:163], v144 offset:96
	s_waitcnt vmcnt(3)
	ds_write_b128 v142, v[102:105] offset:55296
	s_waitcnt lgkmcnt(3)
	v_mfma_f32_32x32x16_f16 v[18:33], v[156:159], v[168:171], v[18:33]
	ds_read_b128 v[156:159], v145 offset:36960
	v_mfma_f32_32x32x16_f16 v[2:17], v[164:167], v[168:171], v[2:17]
	ds_read_b128 v[164:167], v145 offset:41568
	ds_read_b128 v[168:171], v144 offset:4704
	s_waitcnt vmcnt(2)
	ds_write_b128 v142, v[110:113] offset:59904
	s_waitcnt lgkmcnt(3)
	v_mfma_f32_32x32x16_f16 v[50:65], v[156:159], v[160:163], v[50:65]
	s_waitcnt lgkmcnt(2)
	v_mfma_f32_32x32x16_f16 v[34:49], v[164:167], v[160:163], v[34:49]
	s_waitcnt vmcnt(1)
	ds_write_b128 v142, v[118:121] offset:64512
	s_waitcnt lgkmcnt(2)
	v_mfma_f32_32x32x16_f16 v[18:33], v[156:159], v[168:171], v[18:33]
	v_mfma_f32_32x32x16_f16 v[2:17], v[164:167], v[168:171], v[2:17]
	s_waitcnt vmcnt(0)
	ds_write_b128 v143, v[126:129] offset:64512
	s_setprio 0
	s_waitcnt lgkmcnt(0)
	s_barrier
	s_setprio 1
	ds_read_b128 v[156:159], v145 offset:55296
	ds_read_b128 v[160:163], v144 offset:18432
	ds_read_b128 v[164:167], v145 offset:59904
	ds_read_b128 v[168:171], v144 offset:23040
	s_waitcnt lgkmcnt(2)
	v_mfma_f32_32x32x16_f16 v[50:65], v[156:159], v[160:163], v[50:65]
	s_waitcnt lgkmcnt(1)
	v_mfma_f32_32x32x16_f16 v[34:49], v[164:167], v[160:163], v[34:49]
	ds_read_b128 v[160:163], v144 offset:18464
	s_waitcnt lgkmcnt(1)
	v_mfma_f32_32x32x16_f16 v[18:33], v[156:159], v[168:171], v[18:33]
	ds_read_b128 v[156:159], v145 offset:55328
	v_mfma_f32_32x32x16_f16 v[2:17], v[164:167], v[168:171], v[2:17]
	ds_read_b128 v[164:167], v145 offset:59936
	ds_read_b128 v[168:171], v144 offset:23072
	s_waitcnt lgkmcnt(2)
	v_mfma_f32_32x32x16_f16 v[50:65], v[156:159], v[160:163], v[50:65]
	s_waitcnt lgkmcnt(1)
	v_mfma_f32_32x32x16_f16 v[34:49], v[164:167], v[160:163], v[34:49]
	ds_read_b128 v[160:163], v144 offset:18496
	s_waitcnt lgkmcnt(1)
	v_mfma_f32_32x32x16_f16 v[18:33], v[156:159], v[168:171], v[18:33]
	ds_read_b128 v[156:159], v145 offset:55360
	v_mfma_f32_32x32x16_f16 v[2:17], v[164:167], v[168:171], v[2:17]
	ds_read_b128 v[164:167], v145 offset:59968
	ds_read_b128 v[168:171], v144 offset:23104
	s_waitcnt lgkmcnt(2)
	v_mfma_f32_32x32x16_f16 v[50:65], v[156:159], v[160:163], v[50:65]
	s_waitcnt lgkmcnt(1)
	v_mfma_f32_32x32x16_f16 v[34:49], v[164:167], v[160:163], v[34:49]
	ds_read_b128 v[160:163], v144 offset:18528
	s_waitcnt lgkmcnt(1)
	v_mfma_f32_32x32x16_f16 v[18:33], v[156:159], v[168:171], v[18:33]
	ds_read_b128 v[156:159], v145 offset:55392
	v_mfma_f32_32x32x16_f16 v[2:17], v[164:167], v[168:171], v[2:17]
	ds_read_b128 v[164:167], v145 offset:60000
	ds_read_b128 v[168:171], v144 offset:23136
	s_waitcnt lgkmcnt(2)
	v_mfma_f32_32x32x16_f16 v[50:65], v[156:159], v[160:163], v[50:65]
	s_waitcnt lgkmcnt(1)
	v_mfma_f32_32x32x16_f16 v[34:49], v[164:167], v[160:163], v[34:49]
	s_waitcnt lgkmcnt(0)
	v_mfma_f32_32x32x16_f16 v[18:33], v[156:159], v[168:171], v[18:33]
	v_mfma_f32_32x32x16_f16 v[2:17], v[164:167], v[168:171], v[2:17]
	s_setprio 0
	s_nop 1
	s_nop 1
	s_lshl_b32 s16, s0, 7
	v_or_b32_e32 v83, s16, v131
	s_movk_i32 s1, 0x1ff
	v_cmp_lt_i32_e32 vcc, s1, v83
	v_mov_b32_e32 v68, 0x3e38aa3b
	v_mov_b64_e32 v[66:67], s[10:11]
	s_barrier
	s_and_saveexec_b64 s[14:15], vcc
	s_cbranch_execz .LBB0_230
	s_mov_b32 s1, 1.0
	s_cmpk_lt_u32 s16, 0x400
	s_mov_b64 s[16:17], s[8:9]
	s_cbranch_scc1 .LBB0_229
	s_and_b32 s16, s18, 0x3fffff80
	s_mov_b32 s1, 0x3e38aa3b
	s_cmpk_eq_i32 s16, 0x300
	s_mov_b64 s[16:17], s[6:7]
	s_cbranch_scc1 .LBB0_229
	s_cmp_lt_i32 s0, 32
	s_cbranch_scc1 .LBB0_224
	s_cmp_eq_u32 s0, 32
	s_cselect_b64 s[16:17], -1, 0
	s_cbranch_execz .LBB0_225
	s_branch .LBB0_226
